# grid barrier: flat release polling + no s_sleep in the poll loops
# baseline (speedup 1.0000x reference)
; __device__ __forceinline__ unsigned xb_ld(unsigned* p)              { return __hip_atomic_load(p, __ATOMIC_RELAXED, __HIP_MEMORY_SCOPE_AGENT); }
; __device__ __forceinline__ void xcd_barrier_complete(unsigned* bar, unsigned x, unsigned& nloc, unsigned& nx) {
;     ...
;     for (;;) {
;         sum = 0u; cnt = 0u; mine = 0u;
; #pragma unroll
;         for (unsigned j = 0; j < 16; ++j) { const unsigned c = xb_ld(&bar[XB_XCNT(j)]); sum += c; cnt += (c > 0u) ? 1u : 0u; mine = (j == x) ? c : mine; }
;         if (sum == G) break;
;         __builtin_amdgcn_s_sleep(1);
;         if ((++sp & 255u) == 0u) { if (xb_ld(&bar[XB_TMO])) break; if (sp > XB_SPIN_CAP) { atomicAdd(&bar[XB_TMO], 1u); break; } }
;     }
.LBB0_515:
	v_readlane_b32 s6, v254, 24
	v_readlane_b32 s7, v254, 25
	global_load_dword v12, v1, s[88:89] offset:1024 sc1
	global_load_dword v0, v1, s[88:89] offset:1280 sc1
	global_load_dword v2, v1, s[88:89] offset:1536 sc1
	global_load_dword v3, v1, s[88:89] offset:1792 sc1
	global_load_dword v4, v1, s[88:89] offset:2048 sc1
	global_load_dword v5, v1, s[88:89] offset:2304 sc1
	global_load_dword v6, v1, s[88:89] offset:2560 sc1
	global_load_dword v7, v1, s[88:89] offset:2816 sc1
	global_load_dword v8, v1, s[88:89] offset:3072 sc1
	global_load_dword v9, v1, s[88:89] offset:3328 sc1
	global_load_dword v10, v1, s[88:89] offset:3584 sc1
	global_load_dword v11, v1, s[88:89] offset:3840 sc1
	global_load_dword v13, v1, s[6:7] sc1
	v_readlane_b32 s6, v254, 26
	v_readlane_b32 s7, v254, 27
	s_mov_b64 s[8:9], -1
	s_waitcnt vmcnt(11)
	v_add_u32_e32 v17, v0, v12
	s_nop 1
	global_load_dword v14, v1, s[6:7] sc1
	v_readlane_b32 s6, v254, 28
	v_readlane_b32 s7, v254, 29
	s_waitcnt vmcnt(11)
	v_add_u32_e32 v17, v17, v2
	s_waitcnt vmcnt(10)
	v_add_u32_e32 v17, v17, v3
	s_waitcnt vmcnt(9)
	v_add_u32_e32 v17, v17, v4
	s_waitcnt vmcnt(8)
	v_add_u32_e32 v17, v17, v5
	s_waitcnt vmcnt(7)
	v_add_u32_e32 v17, v17, v6
	global_load_dword v15, v1, s[6:7] sc1
	v_readlane_b32 s6, v254, 30
	v_readlane_b32 s7, v254, 31
	s_waitcnt vmcnt(7)
	v_add_u32_e32 v17, v17, v7
	s_waitcnt vmcnt(6)
	v_add_u32_e32 v17, v17, v8
	s_waitcnt vmcnt(5)
	v_add_u32_e32 v17, v17, v9
	s_waitcnt vmcnt(4)
	v_add_u32_e32 v17, v17, v10
	s_waitcnt vmcnt(3)
	v_add_u32_e32 v17, v17, v11
	global_load_dword v16, v1, s[6:7] sc1
	s_waitcnt vmcnt(3)
	v_add_u32_e32 v17, v17, v13
	s_mov_b64 s[6:7], -1
	s_waitcnt vmcnt(2)
	v_add_u32_e32 v17, v17, v14
	s_waitcnt vmcnt(1)
	v_add_u32_e32 v17, v17, v15
	s_waitcnt vmcnt(0)
	v_add_u32_e32 v17, v17, v16
	v_cmp_eq_u32_e32 vcc, s24, v17
	s_cbranch_vccnz .LBB0_514
	s_and_b32 s6, s25, 0xff
	s_cmp_eq_u32 s6, 0
	s_mov_b64 s[6:7], -1
	s_mov_b64 s[18:19], -1
	s_nop 0
	s_cbranch_scc0 .LBB0_519
	v_readlane_b32 s6, v254, 22
	v_readlane_b32 s7, v254, 23
	s_nop 4
	global_load_dword v17, v1, s[6:7] sc1
	s_waitcnt vmcnt(0)
	v_cmp_eq_u32_e32 vcc, 0, v17
	s_cbranch_vccnz .LBB0_521
	s_mov_b64 s[18:19], 0
	s_mov_b64 s[6:7], -1

; __device__ __forceinline__ unsigned xb_ld(unsigned* p)              { return __hip_atomic_load(p, __ATOMIC_RELAXED, __HIP_MEMORY_SCOPE_AGENT); }
; #define XB_SPIN(cond, bar) do { unsigned _sp = 0; while (cond) { __builtin_amdgcn_s_sleep(1); \
;     if ((++_sp & 255u) == 0u) { if (xb_ld(&(bar)[XB_TMO])) break; if (_sp > XB_SPIN_CAP) { atomicAdd(&(bar)[XB_TMO], 1u); break; } } } } while (0)
; __device__ __forceinline__ void xcd_barrier(const XcdBarrier& b) {
;     ...
;         } else {
;             XB_SPIN(xb_ld(&bar[XB_XGEN(b.x)]) == gen, bar);
;             __builtin_amdgcn_fence(__ATOMIC_ACQUIRE, "agent");
;             asm volatile("s_waitcnt vmcnt(0)" ::: "memory");
.LBB0_533:
	s_and_b32 s35, s29, 0xff
	s_mov_b64 s[30:31], -1
	s_cmp_lg_u32 s35, 0
	s_mov_b64 s[40:41], -1
	s_nop 0
	s_cbranch_scc1 .LBB0_536
	v_readlane_b32 s38, v254, 22
	v_readlane_b32 s39, v254, 23
	s_nop 4
	global_load_dword v2, v1, s[38:39] sc1
	s_waitcnt vmcnt(0)
	v_cmp_eq_u32_e32 vcc, 0, v2
	s_cbranch_vccnz .LBB0_538
	s_mov_b64 s[40:41], 0
	s_mov_b64 s[38:39], -1
